# SGU-prep transpose loop: the four serialized row loads per head iteration issued together
# baseline (speedup 1.0000x reference)
; __device__ __forceinline__ bf16_t f2bf(float f) { unsigned u = __float_as_uint(f); u += 0x7FFFu + ((u >> 16) & 1u); return (bf16_t)(u >> 16); }
; __device__ __forceinline__ void UNPACK8(const u32x4 q, float (&f)[8]) { f[0] = bflo(q.x); f[1] = bfhi(q.x); f[2] = bflo(q.y); f[3] = bfhi(q.y); f[4] = bflo(q.z); f[5] = bfhi(q.z); f[6] = bflo(q.w); f[7] = bfhi(q.w); }
; __device__ __forceinline__ void sguprep_chunk(PCP p, int j, LAS unsigned char* lds, int it, int tid) {
;     ...
;         for (int h = 0; h < 4; ++h) {
;             const int d0 = (tid & 15) * 8; const f32x4 g0 = *(const f32x4*)(ng + h * 128 + d0), g1 = *(const f32x4*)(ng + h * 128 + d0 + 4);
; #pragma unroll
;             for (int i = 0; i < 4; ++i) { const int s = (tid >> 4) + 32 * i; const u32x4 vw = *(const u32x4*)(proj + (T0 + s) * 1536 + 1024 + h * 128 + d0); float v[8]; UNPACK8(vw, v); const float rs = rstd[s];
; #pragma unroll
;                 for (int e = 0; e < 4; ++e) { tl[(d0 + e) * 130 + s] = f2bf(v[e] * rs * g0[e]); tl[(d0 + 4 + e) * 130 + s] = f2bf(v[4 + e] * rs * g1[e]); } }
;             __syncthreads();
.LBB0_405:
	v_lshl_add_u64 v[54:55], v[46:47], 0, s[4:5]
	v_add_co_u32_e32 v56, vcc, 0xb200000, v54
	global_load_dwordx4 v[96:99], v[52:53], off
	global_load_dwordx4 v[100:103], v[52:53], off offset:-16
	v_addc_co_u32_e32 v57, vcc, 0, v55, vcc
	global_load_dwordx4 v[104:107], v[56:57], off offset:2048
	ds_read2_b32 v[60:61], v73 offset1:32
	s_mov_b32 s3, 0xb218000
	s_mov_b64 s[16:17], 0x200
	v_lshl_add_u64 v[52:53], v[52:53], 0, s[16:17]
	v_add_co_u32_e32 v84, vcc, s3, v54
	s_nop 1
	v_addc_co_u32_e32 v85, vcc, 0, v55, vcc
	global_load_dwordx4 v[108:111], v[84:85], off offset:2048
	s_mov_b32 s29, 0xb230000
	v_add_co_u32_e32 v84, vcc, s29, v54
	s_nop 1
	v_addc_co_u32_e32 v85, vcc, 0, v55, vcc
	global_load_dwordx4 v[112:115], v[84:85], off offset:2048
	s_mov_b32 s29, 0xb248000
	v_add_co_u32_e32 v84, vcc, s29, v54
	s_nop 1
	v_addc_co_u32_e32 v85, vcc, 0, v55, vcc
	global_load_dwordx4 v[116:119], v[84:85], off offset:2048
	s_waitcnt vmcnt(0)
	v_mov_b32_e32 v0, v96
	v_mov_b32_e32 v1, v97
	v_mov_b32_e32 v2, v98
	v_mov_b32_e32 v3, v99
	v_mov_b32_e32 v4, v100
	v_mov_b32_e32 v5, v101
	v_mov_b32_e32 v6, v102
	v_mov_b32_e32 v7, v103
	v_mov_b32_e32 v56, v104
	v_mov_b32_e32 v57, v105
	v_mov_b32_e32 v58, v106
	v_mov_b32_e32 v59, v107
	v_lshlrev_b32_e32 v62, 16, v56
	s_waitcnt lgkmcnt(0)
	v_mul_f32_e32 v62, v60, v62
	v_mul_f32_e32 v62, v4, v62
	v_bfe_u32 v76, v62, 16, 1
	v_lshlrev_b32_e32 v64, 16, v58
	v_add3_u32 v62, v62, v76, s40
	ds_write_b16_d16_hi v74, v62 offset:1024
	v_mul_f32_e32 v62, v60, v64
	v_and_b32_e32 v56, 0xffff0000, v56
	v_mul_f32_e32 v62, v0, v62
	v_bfe_u32 v64, v62, 16, 1
	v_mul_f32_e32 v56, v60, v56
	v_add3_u32 v62, v62, v64, s40
	v_mul_f32_e32 v56, v5, v56
	ds_write_b16_d16_hi v74, v62 offset:2064
	v_bfe_u32 v62, v56, 16, 1
	v_and_b32_e32 v58, 0xffff0000, v58
	v_add3_u32 v56, v56, v62, s40
	ds_write_b16_d16_hi v74, v56 offset:1284
	v_mul_f32_e32 v56, v60, v58
	v_mul_f32_e32 v56, v1, v56
	v_bfe_u32 v58, v56, 16, 1
	v_lshlrev_b32_e32 v63, 16, v57
	v_add3_u32 v56, v56, v58, s40
	ds_write_b16_d16_hi v74, v56 offset:2324
	v_mul_f32_e32 v56, v60, v63
	v_mul_f32_e32 v56, v6, v56
	v_bfe_u32 v58, v56, 16, 1
	v_lshlrev_b32_e32 v65, 16, v59
	v_add3_u32 v56, v56, v58, s40
	ds_write_b16_d16_hi v74, v56 offset:1544
	v_mul_f32_e32 v56, v60, v65
	v_mul_f32_e32 v56, v2, v56
	v_bfe_u32 v58, v56, 16, 1
	v_and_b32_e32 v57, 0xffff0000, v57
	v_add3_u32 v56, v56, v58, s40
	ds_write_b16_d16_hi v74, v56 offset:2584
	v_mul_f32_e32 v56, v60, v57
	v_mul_f32_e32 v56, v7, v56
	v_bfe_u32 v57, v56, 16, 1
	v_and_b32_e32 v59, 0xffff0000, v59
	v_add3_u32 v56, v56, v57, s40
	ds_write_b16_d16_hi v74, v56 offset:1804
	v_mul_f32_e32 v56, v60, v59
	v_mul_f32_e32 v56, v3, v56
	v_bfe_u32 v57, v56, 16, 1
	v_add3_u32 v56, v56, v57, s40
	ds_write_b16_d16_hi v74, v56 offset:2844
	v_add_co_u32_e32 v56, vcc, s3, v54
	s_mov_b32 s3, 0xb230000
	s_nop 0
	v_addc_co_u32_e32 v57, vcc, 0, v55, vcc
	v_mov_b32_e32 v56, v108
	v_mov_b32_e32 v57, v109
	v_mov_b32_e32 v58, v110
	v_mov_b32_e32 v59, v111
	v_lshlrev_b32_e32 v60, 16, v56
	v_mul_f32_e32 v60, v61, v60
	v_mul_f32_e32 v60, v4, v60
	v_bfe_u32 v65, v60, 16, 1
	v_lshlrev_b32_e32 v63, 16, v58
	v_add3_u32 v60, v60, v65, s40
	ds_write_b16_d16_hi v74, v60 offset:1088
	v_mul_f32_e32 v60, v61, v63
	v_and_b32_e32 v56, 0xffff0000, v56
	v_mul_f32_e32 v60, v0, v60
	v_bfe_u32 v63, v60, 16, 1
	v_mul_f32_e32 v56, v61, v56
	v_add3_u32 v60, v60, v63, s40
	v_mul_f32_e32 v56, v5, v56
	ds_write_b16_d16_hi v74, v60 offset:2128
	v_bfe_u32 v60, v56, 16, 1
	v_and_b32_e32 v58, 0xffff0000, v58
	v_add3_u32 v56, v56, v60, s40
	ds_write_b16_d16_hi v74, v56 offset:1348
	v_mul_f32_e32 v56, v61, v58
	v_mul_f32_e32 v56, v1, v56
	v_bfe_u32 v58, v56, 16, 1
	v_lshlrev_b32_e32 v62, 16, v57
	v_add3_u32 v56, v56, v58, s40
	ds_write_b16_d16_hi v74, v56 offset:2388
	v_mul_f32_e32 v56, v61, v62
	v_mul_f32_e32 v56, v6, v56
	v_bfe_u32 v58, v56, 16, 1
	v_lshlrev_b32_e32 v64, 16, v59
	v_add3_u32 v56, v56, v58, s40
	ds_write_b16_d16_hi v74, v56 offset:1608
	v_mul_f32_e32 v56, v61, v64
	v_mul_f32_e32 v56, v2, v56
	v_bfe_u32 v58, v56, 16, 1
	v_and_b32_e32 v57, 0xffff0000, v57
	v_add3_u32 v56, v56, v58, s40
	ds_write_b16_d16_hi v74, v56 offset:2648
	v_mul_f32_e32 v56, v61, v57
	v_mul_f32_e32 v56, v7, v56
	v_bfe_u32 v57, v56, 16, 1
	v_and_b32_e32 v59, 0xffff0000, v59
	v_add3_u32 v56, v56, v57, s40
	ds_write_b16_d16_hi v74, v56 offset:1868
	v_mul_f32_e32 v56, v61, v59
	v_mul_f32_e32 v56, v3, v56
	v_bfe_u32 v57, v56, 16, 1
	v_add3_u32 v56, v56, v57, s40
	ds_write_b16_d16_hi v74, v56 offset:2908
	v_add_co_u32_e32 v56, vcc, s3, v54
	s_mov_b32 s3, 0xb248000
	s_nop 0
	v_addc_co_u32_e32 v57, vcc, 0, v55, vcc
	v_mov_b32_e32 v56, v112
	v_mov_b32_e32 v57, v113
	v_mov_b32_e32 v58, v114
	v_mov_b32_e32 v59, v115
	v_add_co_u32_e32 v54, vcc, s3, v54
	s_mov_b32 s3, 0x18200000
	s_nop 0
	v_addc_co_u32_e32 v55, vcc, 0, v55, vcc
	v_lshlrev_b32_e32 v62, 16, v58
	v_and_b32_e32 v63, 0xffff0000, v58
	v_lshlrev_b32_e32 v64, 16, v59
	v_and_b32_e32 v65, 0xffff0000, v59
	ds_read2_b32 v[58:59], v73 offset0:64 offset1:96
	v_lshlrev_b32_e32 v60, 16, v56
	v_and_b32_e32 v56, 0xffff0000, v56
	v_lshlrev_b32_e32 v61, 16, v57
	v_and_b32_e32 v57, 0xffff0000, v57
	s_waitcnt lgkmcnt(0)
; #define LAS __attribute__((address_space(3)))
; __device__ __forceinline__ bf16_t f2bf(float f) { unsigned u = __float_as_uint(f); u += 0x7FFFu + ((u >> 16) & 1u); return (bf16_t)(u >> 16); }
; __device__ __forceinline__ void UNPACK8(const u32x4 q, float (&f)[8]) { f[0] = bflo(q.x); f[1] = bfhi(q.x); f[2] = bflo(q.y); f[3] = bfhi(q.y); f[4] = bflo(q.z); f[5] = bfhi(q.z); f[6] = bflo(q.w); f[7] = bfhi(q.w); }
; __device__ __forceinline__ void sguprep_chunk(PCP p, int j, LAS unsigned char* lds, int it, int tid) {
;     ...
;             for (int i = 0; i < 4; ++i) { const int s = (tid >> 4) + 32 * i; const u32x4 vw = *(const u32x4*)(proj + (T0 + s) * 1536 + 1024 + h * 128 + d0); float v[8]; UNPACK8(vw, v); const float rs = rstd[s];
; #pragma unroll
;                 for (int e = 0; e < 4; ++e) { tl[(d0 + e) * 130 + s] = f2bf(v[e] * rs * g0[e]); tl[(d0 + 4 + e) * 130 + s] = f2bf(v[4 + e] * rs * g1[e]); } }
;             __syncthreads();
; #pragma unroll
;             for (int i = 0; i < 4; ++i) { const int d = (tid >> 4) + 32 * i, s0 = (tid & 15) * 8; const LAS unsigned* src = (const LAS unsigned*)(tl + d * 130 + s0);
;                 u32x4 w; w.x = src[0]; w.y = src[1]; w.z = src[2]; w.w = src[3];
;                 *(u32x4*)(vt + ((size_t)it * 128 + d) * 512 + h * 128 + s0) = w; }
;             __syncthreads();
	v_mul_f32_e32 v60, v58, v60
	v_mul_f32_e32 v60, v4, v60
	v_bfe_u32 v76, v60, 16, 1
	v_add3_u32 v60, v60, v76, s40
	ds_write_b16_d16_hi v74, v60 offset:1152
	v_mul_f32_e32 v60, v58, v62
	v_mul_f32_e32 v60, v0, v60
	v_bfe_u32 v62, v60, 16, 1
	v_mul_f32_e32 v56, v58, v56
	v_add3_u32 v60, v60, v62, s40
	v_mul_f32_e32 v56, v5, v56
	ds_write_b16_d16_hi v74, v60 offset:2192
	v_bfe_u32 v60, v56, 16, 1
	v_add3_u32 v56, v56, v60, s40
	ds_write_b16_d16_hi v74, v56 offset:1412
	v_mul_f32_e32 v56, v58, v63
	v_mul_f32_e32 v56, v1, v56
	v_bfe_u32 v60, v56, 16, 1
	v_add3_u32 v56, v56, v60, s40
	ds_write_b16_d16_hi v74, v56 offset:2452
	v_mul_f32_e32 v56, v58, v61
	v_mul_f32_e32 v56, v6, v56
	v_bfe_u32 v60, v56, 16, 1
	v_add3_u32 v56, v56, v60, s40
	ds_write_b16_d16_hi v74, v56 offset:1672
	v_mul_f32_e32 v56, v58, v64
	v_mul_f32_e32 v56, v2, v56
	v_bfe_u32 v60, v56, 16, 1
	v_add3_u32 v56, v56, v60, s40
	ds_write_b16_d16_hi v74, v56 offset:2712
	v_mul_f32_e32 v56, v58, v57
	v_mul_f32_e32 v56, v7, v56
	v_bfe_u32 v57, v56, 16, 1
	v_add3_u32 v56, v56, v57, s40
	ds_write_b16_d16_hi v74, v56 offset:1932
	v_mul_f32_e32 v56, v58, v65
	v_mul_f32_e32 v56, v3, v56
	v_bfe_u32 v57, v56, 16, 1
	v_add3_u32 v56, v56, v57, s40
	ds_write_b16_d16_hi v74, v56 offset:2972
	v_mov_b32_e32 v54, v116
	v_mov_b32_e32 v55, v117
	v_mov_b32_e32 v56, v118
	v_mov_b32_e32 v57, v119
	v_lshlrev_b32_e32 v58, 16, v54
	v_mul_f32_e32 v58, v59, v58
	v_mul_f32_e32 v4, v4, v58
	v_bfe_u32 v58, v4, 16, 1
	v_lshlrev_b32_e32 v61, 16, v56
	v_add3_u32 v4, v4, v58, s40
	ds_write_b16_d16_hi v74, v4 offset:1216
	v_mul_f32_e32 v4, v59, v61
	v_mul_f32_e32 v0, v0, v4
	v_bfe_u32 v4, v0, 16, 1
	v_and_b32_e32 v54, 0xffff0000, v54
	v_add3_u32 v0, v0, v4, s40
	ds_write_b16_d16_hi v74, v0 offset:2256
	v_mul_f32_e32 v0, v59, v54
	v_mul_f32_e32 v0, v5, v0
	v_bfe_u32 v4, v0, 16, 1
	v_and_b32_e32 v56, 0xffff0000, v56
	v_add3_u32 v0, v0, v4, s40
	ds_write_b16_d16_hi v74, v0 offset:1476
	v_mul_f32_e32 v0, v59, v56
	v_mul_f32_e32 v0, v1, v0
	v_bfe_u32 v1, v0, 16, 1
	v_lshlrev_b32_e32 v60, 16, v55
	v_add3_u32 v0, v0, v1, s40
	ds_write_b16_d16_hi v74, v0 offset:2516
	v_mul_f32_e32 v0, v59, v60
	v_mul_f32_e32 v0, v6, v0
	v_bfe_u32 v1, v0, 16, 1
	v_lshlrev_b32_e32 v62, 16, v57
	v_add3_u32 v0, v0, v1, s40
	ds_write_b16_d16_hi v74, v0 offset:1736
	v_mul_f32_e32 v0, v59, v62
	v_mul_f32_e32 v0, v2, v0
	v_bfe_u32 v1, v0, 16, 1
	v_and_b32_e32 v55, 0xffff0000, v55
	v_add3_u32 v0, v0, v1, s40
	ds_write_b16_d16_hi v74, v0 offset:2776
	v_mul_f32_e32 v0, v59, v55
	v_mul_f32_e32 v0, v7, v0
	v_bfe_u32 v1, v0, 16, 1
	v_and_b32_e32 v57, 0xffff0000, v57
	v_add3_u32 v0, v0, v1, s40
	ds_write_b16_d16_hi v74, v0 offset:1996
	v_mul_f32_e32 v0, v59, v57
	v_mul_f32_e32 v0, v3, v0
	v_bfe_u32 v1, v0, 16, 1
	v_add3_u32 v0, v0, v1, s40
	v_add_u32_e32 v2, v71, v72
	ds_write_b16_d16_hi v74, v0 offset:3036
	v_add_u32_e32 v0, 0x400, v2
	v_add_u32_e32 v2, 0x408, v2
	s_waitcnt lgkmcnt(0)
	s_barrier
	ds_read2_b32 v[0:1], v0 offset1:1
	ds_read2_b32 v[2:3], v2 offset1:1
	v_lshl_add_u64 v[4:5], v[48:49], 0, s[4:5]
	v_add_co_u32_e32 v6, vcc, s3, v4
	s_mov_b32 s3, 0x18208000
	s_nop 0
	v_addc_co_u32_e32 v7, vcc, 0, v5, vcc
	s_waitcnt lgkmcnt(0)
	global_store_dwordx4 v[6:7], v[0:3], off
	v_add_co_u32_e32 v6, vcc, s3, v4
	s_nop 0
	v_add_u32_e32 v0, 0x400, v75
	v_add_u32_e32 v2, 0x408, v75
	ds_read2_b32 v[0:1], v0 offset1:1
	ds_read2_b32 v[2:3], v2 offset1:1
	v_addc_co_u32_e32 v7, vcc, 0, v5, vcc
	s_mov_b32 s3, 0x18210000
	s_add_u32 s4, s4, 0x100
	s_waitcnt lgkmcnt(0)
	global_store_dwordx4 v[6:7], v[0:3], off
	v_add_co_u32_e32 v6, vcc, s3, v4
	s_nop 0
	v_add_u32_e32 v0, 0x2480, v75
	v_add_u32_e32 v2, 0x2488, v75
	ds_read2_b32 v[0:1], v0 offset1:1
	ds_read2_b32 v[2:3], v2 offset1:1
	v_addc_co_u32_e32 v7, vcc, 0, v5, vcc
	s_mov_b32 s3, 0x18218000
	v_add_co_u32_e32 v4, vcc, s3, v4
	s_waitcnt lgkmcnt(0)
	global_store_dwordx4 v[6:7], v[0:3], off
	s_addc_u32 s5, s5, 0
	v_addc_co_u32_e32 v5, vcc, 0, v5, vcc
	v_add_u32_e32 v0, 0x4500, v75
	v_add_u32_e32 v2, 0x4508, v75
	ds_read2_b32 v[0:1], v0 offset1:1
	ds_read2_b32 v[2:3], v2 offset1:1
	s_cmpk_lg_i32 s4, 0x400
	s_waitcnt lgkmcnt(0)
	global_store_dwordx4 v[4:5], v[0:3], off
	s_barrier
	s_cbranch_scc1 .LBB0_405
	v_readlane_b32 s4, v252, 36
	v_readlane_b32 s5, v252, 37
	s_add_i32 s2, s2, s34
	s_cmpk_lt_i32 s2, 0x100
	v_lshl_add_u64 v[46:47], v[46:47], 0, s[4:5]
	v_readlane_b32 s4, v252, 46
	v_readlane_b32 s5, v252, 47
	s_barrier
	s_nop 0
	v_lshl_add_u64 v[48:49], v[48:49], 0, s[4:5]
	s_cbranch_scc1 .LBB0_326
	s_branch .LBB0_421
